# baseline (speedup 1.0000x reference)
; template <int EPI>
; __device__ __forceinline__ void phase_gemm(const Params& p, const GemmDesc& d, char* shmc) {
;     ...
;       float* top = reinterpret_cast<float*>(shmc);
;       float* bot = top + 64 * 144;
;       u16* stg = reinterpret_cast<u16*>(shmc + 73728);
;       const int ch0 = pn * 128;
;       const float* cwp = p.conv_w + (size_t)d.layer * 3 * DFF;
;       const float* cbp = p.conv_b + (size_t)d.layer * DFF;
;       float cw[2][4];
; #pragma unroll
;       for (int n = 0; n < 2; ++n) {
;         const int chx = ch0 + ewc * 32 + n * 16 + efr;
;         cw[n][0] = cwp[chx]; cw[n][1] = cwp[DFF + chx]; cw[n][2] = cwp[2 * DFF + chx]; cw[n][3] = cbp[chx];
;       }
;       const float* rsl = reinterpret_cast<const float*>(shmc + 143360);
;       f32x4 rsv[2][4];
; #pragma unroll
;       for (int ai = 0; ai < 2; ++ai)
; #pragma unroll
;         for (int m = 0; m < 4; ++m)
;           rsv[ai][m] = *reinterpret_cast<const f32x4*>(rsl + ai * HALF + ewr * 64 + m * 16 + efq * 4);
; #pragma unroll
;       for (int ai = 0; ai < 2; ++ai)
; #pragma unroll
;         for (int m = 0; m < 4; ++m) {
;           const f32x4 rs4 = rsv[ai][m];
; #pragma unroll
;           for (int n = 0; n < 2; ++n) {
;             acc[ai][0][m][n] *= rs4;
;             acc[ai][1][m][n] *= rs4;
;             const int s = ai * 32 + ewr * 16 + m * 4 + efq;
;             const int col = ewc * 32 + n * 16 + efr;
;             top[s * 144 + col] = acc[ai][0][m][n][0];
;             bot[s * 144 + col] = acc[ai][0][m][n][3];
;           }
;         }
;       __syncthreads();
.LBB0_299:
	s_mov_b32 s98, 0x3e8ba43f
	s_or_b64 exec, exec, s[8:9]
	v_mov_b32_e32 v38, v1
	s_movk_i32 s8, 0x60
	v_and_b32_e32 v177, 15, v38
	v_lshrrev_b32_e32 v30, 1, v38
	s_lshl_b32 s62, s34, 7
	v_and_or_b32 v162, v30, s8, v177
	v_or_b32_e32 v200, s62, v162
	v_ashrrev_i32_e32 v201, 31, v200
	v_lshlrev_b64 v[30:31], 2, v[200:201]
	v_lshl_add_u64 v[32:33], s[44:45], 0, v[30:31]
	v_add_co_u32_e32 v34, vcc, 0x5000, v32
	v_lshl_add_u64 v[30:31], s[46:47], 0, v[30:31]
	s_nop 0
	v_addc_co_u32_e32 v35, vcc, 0, v33, vcc
	v_add_co_u32_e32 v36, vcc, 0xb000, v32
	v_ashrrev_i32_e32 v175, 4, v38
	s_nop 0
	v_addc_co_u32_e32 v37, vcc, 0, v33, vcc
	global_load_dword v215, v[32:33], off
	global_load_dword v217, v[34:35], off offset:2048
	global_load_dword v216, v[36:37], off
	global_load_dword v208, v[36:37], off offset:64
	global_load_dword v210, v[34:35], off offset:2112
	global_load_dword v209, v[32:33], off offset:64
	global_load_dword v218, v[30:31], off
	global_load_dword v207, v[30:31], off offset:64
	v_bfe_u32 v178, v38, 8, 1
	v_and_b32_e32 v179, 3, v175
	v_lshlrev_b32_e32 v30, 8, v178
	v_lshlrev_b32_e32 v31, 4, v179
	v_add3_u32 v30, s76, v30, v31
	v_lshl_or_b32 v220, v178, 4, v179
	s_movk_i32 s8, 0x90
	ds_read_b128 v[62:65], v30
	ds_read_b128 v[54:57], v30 offset:64
	ds_read_b128 v[50:53], v30 offset:128
	ds_read_b128 v[46:49], v30 offset:192
	ds_read_b128 v[42:45], v30 offset:512
	ds_read_b128 v[38:41], v30 offset:576
	ds_read_b128 v[34:37], v30 offset:640
	ds_read_b128 v[30:33], v30 offset:704
	v_mad_u32_u24 v178, v220, s8, v162
	v_lshl_add_u32 v211, v178, 2, 0
	s_waitcnt lgkmcnt(0)
	v_pk_mul_f32 v[196:197], v[144:145], v[56:57]
	v_pk_mul_f32 v[198:199], v[142:143], v[54:55]
	v_pk_mul_f32 v[144:145], v[134:135], v[54:55]
	v_add_u32_e32 v134, 0x800, v211
	v_pk_mul_f32 v[190:191], v[128:129], v[52:53]
	v_pk_mul_f32 v[188:189], v[110:111], v[46:47]
	v_pk_mul_f32 v[128:129], v[102:103], v[46:47]
	v_add_u32_e32 v102, 0x1800, v211
	v_pk_mul_f32 v[142:143], v[136:137], v[56:57]
	ds_write2_b32 v134, v198, v144 offset0:64 offset1:80
	v_add_u32_e32 v134, 0x9800, v211
	v_pk_mul_f32 v[192:193], v[126:127], v[50:51]
	v_pk_mul_f32 v[136:137], v[118:119], v[50:51]
	v_add_u32_e32 v118, 0x1000, v211
	v_pk_mul_f32 v[186:187], v[112:113], v[48:49]
	v_pk_mul_f32 v[126:127], v[104:105], v[48:49]
	ds_write2_b32 v102, v188, v128 offset0:192 offset1:208
	v_add_u32_e32 v102, 0xa800, v211
	ds_write2_b32 v134, v197, v143 offset0:64 offset1:80
	v_pk_mul_f32 v[134:135], v[120:121], v[52:53]
	ds_write2_b32 v118, v192, v136 offset0:128 offset1:144
	v_add_u32_e32 v118, 0xa000, v211
	ds_write2_b32 v102, v187, v127 offset0:192 offset1:208
	v_pk_mul_f32 v[184:185], v[154:155], v[42:43]
	v_pk_mul_f32 v[120:121], v[150:151], v[42:43]
	v_add_u32_e32 v102, 0x4800, v211
	ds_write2_b32 v118, v191, v135 offset0:128 offset1:144
	v_pk_mul_f32 v[182:183], v[156:157], v[44:45]
	v_pk_mul_f32 v[118:119], v[152:153], v[44:45]
	ds_write2_b32 v102, v184, v120 offset1:16
	v_add_u32_e32 v102, 0xd800, v211
	v_pk_mul_f32 v[154:155], v[106:107], v[30:31]
	v_pk_mul_f32 v[98:99], v[98:99], v[30:31]
	v_add_u32_e32 v106, 0x6000, v211
	ds_write2_b32 v102, v183, v119 offset1:16
	v_pk_mul_f32 v[180:181], v[138:139], v[38:39]
	v_pk_mul_f32 v[112:113], v[130:131], v[38:39]
	v_add_u32_e32 v102, 0x5000, v211
	v_pk_mul_f32 v[152:153], v[108:109], v[32:33]
	v_pk_mul_f32 v[100:101], v[100:101], v[32:33]
	ds_write2_b32 v106, v154, v98 offset0:192 offset1:208
	v_add_u32_e32 v106, 0xf000, v211
	s_movk_i32 s8, 0x240
	v_pk_mul_f32 v[202:203], v[160:161], v[64:65]
	v_pk_mul_f32 v[194:195], v[158:159], v[62:63]
	v_pk_mul_f32 v[146:147], v[146:147], v[62:63]
	v_pk_mul_f32 v[178:179], v[140:141], v[40:41]
	v_pk_mul_f32 v[110:111], v[132:133], v[40:41]
	ds_write2_b32 v102, v180, v112 offset0:64 offset1:80
	v_add_u32_e32 v102, 0xe000, v211
	v_pk_mul_f32 v[160:161], v[122:123], v[34:35]
	v_pk_mul_f32 v[104:105], v[114:115], v[34:35]
	v_add_u32_e32 v114, 0x5800, v211
	ds_write2_b32 v106, v153, v101 offset0:192 offset1:208
	v_mad_u32_u24 v106, v220, s8, 0
	v_pk_mul_f32 v[158:159], v[148:149], v[64:65]
	ds_write2_b32 v211, v194, v146 offset1:16
	v_add_u32_e32 v148, 0x9000, v211
	ds_write2_b32 v102, v179, v111 offset0:64 offset1:80
	v_pk_mul_f32 v[156:157], v[124:125], v[36:37]
	v_pk_mul_f32 v[102:103], v[116:117], v[36:37]
	ds_write2_b32 v114, v160, v104 offset0:128 offset1:144
	v_add_u32_e32 v114, 0xe800, v211
	v_cmp_eq_u32_e64 s[10:11], 0, v220
	v_cmp_ne_u32_e32 vcc, 0, v220
	v_mov_b32_e32 v213, 0
	v_lshl_add_u32 v211, v162, 2, v106
	v_mov_b32_e32 v224, 0
	ds_write2_b32 v148, v203, v159 offset1:16
	ds_write2_b32 v114, v157, v103 offset0:128 offset1:144
	s_waitcnt lgkmcnt(0)
	s_barrier
; __device__ __forceinline__ float erf_f32(float x) {
;   const float ax = fabsf(x);
;   const float t = __frcp_rn(fmaf(0.3275911f, ax, 1.0f));
;   float poly = fmaf(1.061405429f, t, -1.453152027f);
;   poly = fmaf(poly, t, 1.421413741f);
;   poly = fmaf(poly, t, -0.284496736f);
;   poly = fmaf(poly, t, 0.254829592f);
;   const float y = 1.0f - poly * t * __expf(-ax * ax);
; template <int EPI>
; __device__ __forceinline__ void phase_gemm(const Params& p, const GemmDesc& d, char* shmc) {
;     ...
;       float gp[2][4][2], gn[2][4][2];
; #pragma unroll
;       for (int ai = 0; ai < 2; ++ai)
; #pragma unroll
;         for (int m = 0; m < 4; ++m)
; #pragma unroll
;           for (int n = 0; n < 2; ++n) {
;             const int s = ai * 32 + ewr * 16 + m * 4 + efq;
;             const int col = ewc * 32 + n * 16 + efr;
;             gp[ai][m][n] = (s > 0) ? bot[(s - 1) * 144 + col] : 0.f;
;             gn[ai][m][n] = (s < 63) ? top[(s + 1) * 144 + col] : 0.f;
;           }
;       float* edge = p.edge + (size_t)pm * 6 * DFF;
; #pragma unroll
;       for (int n = 0; n < 2; ++n) {
;         const int col = ewc * 32 + n * 16 + efr;
;         const int ch = ch0 + col;
;         const float w0 = cw[n][0], w1 = cw[n][1], w2 = cw[n][2], cb = cw[n][3];
; #pragma unroll
;         for (int ai = 0; ai < 2; ++ai)
; #pragma unroll
;           for (int m = 0; m < 4; ++m) {
;             const int s = ai * 32 + ewr * 16 + m * 4 + efq;
;             const f32x4 g = acc[ai][0][m][n];
;             const f32x4 v = acc[ai][1][m][n];
;             const float c0 = w0 * gp[ai][m][n] + w1 * g[0] + w2 * g[1] + cb;
;             const float c1 = w0 * g[0] + w1 * g[1] + w2 * g[2] + cb;
;             const float c2 = w0 * g[1] + w1 * g[2] + w2 * g[3] + cb;
;             const float c3 = w0 * g[2] + w1 * g[3] + w2 * gn[ai][m][n] + cb;
;             u16* sp = stg + (s * 4) * 136 + col;
;             sp[0] = f2bf(gelu_exact(c0) * v[0]);
;             sp[136] = f2bf(gelu_exact(c1) * v[1]);
;             sp[272] = f2bf(gelu_exact(c2) * v[2]);
;             sp[408] = f2bf(gelu_exact(c3) * v[3]);
;             if (s == 0) {
;               edge[0 * DFF + ch] = c0; edge[1 * DFF + ch] = g[0]; edge[2 * DFF + ch] = v[0];
;             }
;             if (s == 63) {
;               edge[3 * DFF + ch] = c3; edge[4 * DFF + ch] = g[3]; edge[5 * DFF + ch] = v[3];
;             }
;           }
	s_and_saveexec_b64 s[8:9], vcc
	ds_read_b32 v224, v211 offset:36288
	s_or_b64 exec, exec, s[8:9]
	ds_read_b32 v223, v211 offset:576
	s_and_saveexec_b64 s[8:9], vcc
	ds_read_b32 v213, v211 offset:36352
	s_or_b64 exec, exec, s[8:9]
	v_add_u32_e32 v106, 0x9400, v211
	ds_read2_b32 v[150:151], v106 offset0:176 offset1:192
	v_add_u32_e32 v106, 0x800, v211
	ds_read2_b32 v[148:149], v106 offset0:208 offset1:224
	v_add_u32_e32 v106, 0x9e00, v211
	ds_read2_b32 v[140:141], v106 offset0:112 offset1:128
	v_add_u32_e32 v106, 0x1400, v211
	ds_read2_b32 v[138:139], v106 offset0:16 offset1:32
	v_add_u32_e32 v106, 0xa800, v211
	ds_read2_b32 v[132:133], v106 offset0:48 offset1:64
	v_add_u32_e32 v106, 0x1c00, v211
	ds_read2_b32 v[130:131], v106 offset0:80 offset1:96
	v_add_u32_e32 v106, 0xd400, v211
	ds_read2_b32 v[124:125], v106 offset0:112 offset1:128
	v_add_u32_e32 v106, 0x4800, v211
	ds_read2_b32 v[122:123], v106 offset0:144 offset1:160
	v_add_u32_e32 v106, 0xdc00, v211
	ds_read2_b32 v[116:117], v106 offset0:176 offset1:192
	v_add_u32_e32 v106, 0x5000, v211
	ds_read2_b32 v[114:115], v106 offset0:208 offset1:224
	v_add_u32_e32 v106, 0xe600, v211
	ds_read2_b32 v[108:109], v106 offset0:112 offset1:128
	v_add_u32_e32 v106, 0x5c00, v211
	ds_read2_b32 v[106:107], v106 offset0:16 offset1:32
	ds_read_b32 v214, v211 offset:640
	ds_read_b32 v221, v211 offset:61632
	v_cmp_eq_u32_e64 s[8:9], 19, v220
	v_cmp_ne_u32_e32 vcc, 19, v220
	v_add_u32_e32 v222, 0x6300, v211
	v_mov_b32_e32 v211, 0
	v_mov_b32_e32 v219, 0
	s_and_saveexec_b64 s[64:65], vcc
	ds_read_b32 v219, v222 offset:576
	s_or_b64 exec, exec, s[64:65]
	ds_read_b32 v212, v222 offset:36352
	s_and_saveexec_b64 s[64:65], vcc
	ds_read_b32 v211, v222 offset:640
	s_or_b64 exec, exec, s[64:65]
	s_mul_hi_i32 s34, s14, 0x21000
	s_mul_i32 s14, s14, 0x21000
	v_readlane_b32 s72, v246, 15
	v_readlane_b32 s73, v246, 16
	s_add_u32 s64, s72, s14
	s_addc_u32 s65, s73, s34
	v_pk_mul_f32 v[226:227], v[96:97], v[64:65]
	v_pk_mul_f32 v[96:97], v[94:95], v[62:63]
	v_lshl_add_u64 v[94:95], v[200:201], 2, s[64:65]
	s_waitcnt lgkmcnt(14)
	s_waitcnt vmcnt(0)
	v_fma_f32 v200, v215, v224, v218
	v_fmac_f32_e32 v200, v217, v194
	v_mul_f32_e32 v224, v217, v202
	v_fmac_f32_e32 v200, v216, v195
	v_fma_f32 v201, v217, v195, v218
	v_fmac_f32_e32 v224, v215, v195
	v_fmac_f32_e32 v201, v215, v194
	v_fmac_f32_e32 v224, v216, v203
	v_fma_f32 v203, v217, v203, v218
	v_fmac_f32_e32 v201, v216, v202
	v_fmac_f32_e32 v203, v215, v202
	v_mul_f32_e32 v202, 0x3f596d27, v200
	v_fmac_f32_e32 v203, v216, v223
	v_fma_f32 v223, |v202|, s98, 1.0
	v_add_f32_e32 v195, v218, v224
	s_add_i32 s14, 0, 0x12000
	v_lshl_add_u32 v222, v162, 1, s14
	v_rcp_f32_e32 v223, v223
	v_mul_f32_e64 v225, |v202|, -|v202|
	v_fmamk_f32 v224, v223, 0x3f87dc22, v206
	v_fmaak_f32 v224, v224, v223, 0x3fb5f0e3
	v_exp_f32_e32 v225, v225
	v_fmaak_f32 v224, v224, v223, 0xbe91a98e
	v_fmaak_f32 v224, v224, v223, 0x3e827906
	v_mul_f32_e32 v223, v223, v224
	v_fma_f32 v202, -v225, v223, 1.0
	v_mul_f32_e32 v223, 0x3f596d27, v201
	s_movk_i32 s34, 0x440
	v_fma_f32 v224, |v223|, s98, 1.0
	v_mad_u32_u24 v228, v220, s34, v222
	v_mul_f32_e32 v229, 0.5, v200
	v_fma_f32 v202, |v229|, v202, v229
	v_mul_f32_e32 v202, v96, v202
	v_cvt_pk_bf16_f32 v202, v202, s0
	ds_write_b16 v228, v202
	v_rcp_f32_e32 v202, v224
	v_mul_f32_e64 v225, |v223|, -|v223|
	v_fmamk_f32 v224, v202, 0x3f87dc22, v206
	v_fmaak_f32 v224, v224, v202, 0x3fb5f0e3
	v_exp_f32_e32 v225, v225
	v_fmaak_f32 v224, v224, v202, 0xbe91a98e
	v_fmaak_f32 v224, v224, v202, 0x3e827906
	v_mul_f32_e32 v202, v202, v224
	v_fma_f32 v202, -v225, v202, 1.0
	v_mul_f32_e32 v201, 0.5, v201
	v_fma_f32 v201, |v201|, v202, v201
	v_mul_f32_e32 v97, v97, v201
	v_mul_f32_e32 v201, 0x3f596d27, v195
	v_fma_f32 v202, |v201|, s98, 1.0
	v_cvt_pk_bf16_f32 v97, v97, s0
	ds_write_b16 v228, v97 offset:272
	v_mul_f32_e32 v97, 0.5, v195
	v_rcp_f32_e32 v195, v202
	v_mul_f32_e64 v223, |v201|, -|v201|
	v_fmamk_f32 v202, v195, 0x3f87dc22, v206
	v_fmaak_f32 v202, v202, v195, 0x3fb5f0e3
	v_exp_f32_e32 v223, v223
	v_fmaak_f32 v202, v202, v195, 0xbe91a98e
	v_fmaak_f32 v202, v202, v195, 0x3e827906
	v_mul_f32_e32 v195, v195, v202
	v_fma_f32 v195, -v223, v195, 1.0
	v_fma_f32 v97, |v97|, v195, v97
	v_mul_f32_e32 v195, 0x3f596d27, v203
	v_fma_f32 v201, |v195|, s98, 1.0
	v_mul_f32_e32 v97, v226, v97
	v_cvt_pk_bf16_f32 v97, v97, s0
	ds_write_b16 v228, v97 offset:544
	v_mul_f32_e32 v97, 0.5, v203
	v_rcp_f32_e32 v201, v201
	v_mul_f32_e64 v203, |v195|, -|v195|
	v_fmamk_f32 v202, v201, 0x3f87dc22, v206
	v_fmaak_f32 v202, v202, v201, 0x3fb5f0e3
	v_exp_f32_e32 v203, v203
	v_fmaak_f32 v202, v202, v201, 0xbe91a98e
	v_fmaak_f32 v202, v202, v201, 0x3e827906
	v_mul_f32_e32 v201, v201, v202
	v_fma_f32 v195, -v203, v201, 1.0
	v_fma_f32 v97, |v97|, v195, v97
	v_mul_f32_e32 v97, v227, v97
	v_cvt_pk_bf16_f32 v97, v97, s0
	v_readlane_b32 s74, v246, 17
	v_readlane_b32 s75, v246, 18
	ds_write_b16 v228, v97 offset:816
	s_and_saveexec_b64 s[78:79], s[10:11]
	s_cbranch_execz .LBB0_309
	global_store_dword v[94:95], v200, off
	v_add_co_u32_e32 v200, vcc, 0x5000, v94
	s_nop 1
	v_addc_co_u32_e32 v201, vcc, 0, v95, vcc
	global_store_dword v[200:201], v194, off offset:2048
	v_add_co_u32_e32 v194, vcc, 0xb000, v94
	s_nop 1
	v_addc_co_u32_e32 v195, vcc, 0, v95, vcc
	global_store_dword v[194:195], v96, off

; template <int EPI>
; __device__ __forceinline__ void phase_gemm(const Params& p, const GemmDesc& d, char* shmc) {
;     ...
;       float* top = reinterpret_cast<float*>(shmc);
;       float* bot = top + 64 * 144;
;       u16* stg = reinterpret_cast<u16*>(shmc + 73728);
;       const int ch0 = pn * 128;
;       const float* cwp = p.conv_w + (size_t)d.layer * 3 * DFF;
;       const float* cbp = p.conv_b + (size_t)d.layer * DFF;
;       float cw[2][4];
; #pragma unroll
;       for (int n = 0; n < 2; ++n) {
;         const int chx = ch0 + ewc * 32 + n * 16 + efr;
;         cw[n][0] = cwp[chx]; cw[n][1] = cwp[DFF + chx]; cw[n][2] = cwp[2 * DFF + chx]; cw[n][3] = cbp[chx];
;       }
;       const float* rsl = reinterpret_cast<const float*>(shmc + 143360);
;       f32x4 rsv[2][4];
; #pragma unroll
;       for (int ai = 0; ai < 2; ++ai)
; #pragma unroll
;         for (int m = 0; m < 4; ++m)
;           rsv[ai][m] = *reinterpret_cast<const f32x4*>(rsl + ai * HALF + ewr * 64 + m * 16 + efq * 4);
; #pragma unroll
;       for (int ai = 0; ai < 2; ++ai)
; #pragma unroll
;         for (int m = 0; m < 4; ++m) {
;           const f32x4 rs4 = rsv[ai][m];
; #pragma unroll
;           for (int n = 0; n < 2; ++n) {
;             acc[ai][0][m][n] *= rs4;
;             acc[ai][1][m][n] *= rs4;
;             const int s = ai * 32 + ewr * 16 + m * 4 + efq;
;             const int col = ewc * 32 + n * 16 + efr;
;             top[s * 144 + col] = acc[ai][0][m][n][0];
;             bot[s * 144 + col] = acc[ai][0][m][n][3];
;           }
;         }
;       __syncthreads();
.LBB0_1156:
	s_mov_b32 s98, 0x3e8ba43f
	s_or_b64 exec, exec, s[8:9]
	v_mov_b32_e32 v38, v1
	s_lshl_b32 s54, s34, 7
	v_and_b32_e32 v177, 15, v38
	v_lshrrev_b32_e32 v30, 1, v38
	v_and_or_b32 v162, v30, s79, v177
	v_or_b32_e32 v200, s54, v162
	v_ashrrev_i32_e32 v201, 31, v200
	v_lshlrev_b64 v[30:31], 2, v[200:201]
	v_lshl_add_u64 v[32:33], s[22:23], 0, v[30:31]
	v_add_co_u32_e32 v34, vcc, 0x5000, v32
	v_lshl_add_u64 v[30:31], s[24:25], 0, v[30:31]
	s_nop 0
	v_addc_co_u32_e32 v35, vcc, 0, v33, vcc
	v_add_co_u32_e32 v36, vcc, 0xb000, v32
	v_ashrrev_i32_e32 v175, 4, v38
	s_nop 0
	v_addc_co_u32_e32 v37, vcc, 0, v33, vcc
	global_load_dword v215, v[32:33], off
	global_load_dword v217, v[34:35], off offset:2048
	global_load_dword v216, v[36:37], off
	global_load_dword v218, v[30:31], off
	v_or_b32_e32 v30, 16, v200
	v_ashrrev_i32_e32 v31, 31, v30
	v_lshlrev_b64 v[30:31], 2, v[30:31]
	v_lshl_add_u64 v[32:33], s[22:23], 0, v[30:31]
	v_add_co_u32_e32 v34, vcc, s80, v32
	v_lshl_add_u64 v[30:31], s[24:25], 0, v[30:31]
	s_nop 0
	v_addc_co_u32_e32 v35, vcc, 0, v33, vcc
	v_add_co_u32_e32 v36, vcc, s81, v32
	v_bfe_u32 v178, v38, 8, 1
	s_nop 0
	v_addc_co_u32_e32 v37, vcc, 0, v33, vcc
	global_load_dword v208, v[32:33], off
	global_load_dword v210, v[34:35], off offset:2048
	global_load_dword v209, v[36:37], off
	global_load_dword v207, v[30:31], off
	v_and_b32_e32 v179, 3, v175
	v_lshlrev_b32_e32 v30, 8, v178
	v_lshlrev_b32_e32 v31, 4, v179
	v_add3_u32 v30, s63, v30, v31
	v_lshl_or_b32 v220, v178, 4, v179
	ds_read_b128 v[62:65], v30
	ds_read_b128 v[54:57], v30 offset:64
	ds_read_b128 v[50:53], v30 offset:128
	ds_read_b128 v[46:49], v30 offset:192
	ds_read_b128 v[42:45], v30 offset:512
	ds_read_b128 v[38:41], v30 offset:576
	ds_read_b128 v[34:37], v30 offset:640
	ds_read_b128 v[30:33], v30 offset:704
	v_mad_u32_u24 v178, v220, s82, v162
	v_lshl_add_u32 v211, v178, 2, 0
	s_waitcnt lgkmcnt(0)
	v_pk_mul_f32 v[196:197], v[144:145], v[56:57]
	v_pk_mul_f32 v[198:199], v[142:143], v[54:55]
	v_pk_mul_f32 v[144:145], v[134:135], v[54:55]
	v_add_u32_e32 v134, 0x800, v211
	v_pk_mul_f32 v[190:191], v[128:129], v[52:53]
	v_pk_mul_f32 v[188:189], v[110:111], v[46:47]
	v_pk_mul_f32 v[128:129], v[102:103], v[46:47]
	v_add_u32_e32 v102, 0x1800, v211
	v_pk_mul_f32 v[142:143], v[136:137], v[56:57]
	ds_write2_b32 v134, v198, v144 offset0:64 offset1:80
	v_add_u32_e32 v134, 0x9800, v211
	v_pk_mul_f32 v[192:193], v[126:127], v[50:51]
	v_pk_mul_f32 v[136:137], v[118:119], v[50:51]
	v_add_u32_e32 v118, 0x1000, v211
	v_pk_mul_f32 v[186:187], v[112:113], v[48:49]
	v_pk_mul_f32 v[126:127], v[104:105], v[48:49]
	ds_write2_b32 v102, v188, v128 offset0:192 offset1:208
	v_add_u32_e32 v102, 0xa800, v211
	ds_write2_b32 v134, v197, v143 offset0:64 offset1:80
	v_pk_mul_f32 v[134:135], v[120:121], v[52:53]
	ds_write2_b32 v118, v192, v136 offset0:128 offset1:144
	v_add_u32_e32 v118, 0xa000, v211
	ds_write2_b32 v102, v187, v127 offset0:192 offset1:208
	v_pk_mul_f32 v[184:185], v[154:155], v[42:43]
	v_pk_mul_f32 v[120:121], v[150:151], v[42:43]
	v_add_u32_e32 v102, 0x4800, v211
	ds_write2_b32 v118, v191, v135 offset0:128 offset1:144
	v_pk_mul_f32 v[182:183], v[156:157], v[44:45]
	v_pk_mul_f32 v[118:119], v[152:153], v[44:45]
	ds_write2_b32 v102, v184, v120 offset1:16
	v_add_u32_e32 v102, 0xd800, v211
	v_pk_mul_f32 v[154:155], v[106:107], v[30:31]
	v_pk_mul_f32 v[98:99], v[98:99], v[30:31]
	v_add_u32_e32 v106, 0x6000, v211
	ds_write2_b32 v102, v183, v119 offset1:16
	v_pk_mul_f32 v[180:181], v[138:139], v[38:39]
	v_pk_mul_f32 v[112:113], v[130:131], v[38:39]
	v_add_u32_e32 v102, 0x5000, v211
	v_pk_mul_f32 v[152:153], v[108:109], v[32:33]
	v_pk_mul_f32 v[100:101], v[100:101], v[32:33]
	ds_write2_b32 v106, v154, v98 offset0:192 offset1:208
	v_add_u32_e32 v106, 0xf000, v211
	v_pk_mul_f32 v[202:203], v[160:161], v[64:65]
	v_pk_mul_f32 v[194:195], v[158:159], v[62:63]
	v_pk_mul_f32 v[146:147], v[146:147], v[62:63]
	v_pk_mul_f32 v[178:179], v[140:141], v[40:41]
	v_pk_mul_f32 v[110:111], v[132:133], v[40:41]
	ds_write2_b32 v102, v180, v112 offset0:64 offset1:80
	v_add_u32_e32 v102, 0xe000, v211
	v_pk_mul_f32 v[160:161], v[122:123], v[34:35]
	v_pk_mul_f32 v[104:105], v[114:115], v[34:35]
	v_add_u32_e32 v114, 0x5800, v211
	ds_write2_b32 v106, v153, v101 offset0:192 offset1:208
	v_mad_u32_u24 v106, v220, s83, 0
	v_pk_mul_f32 v[158:159], v[148:149], v[64:65]
	ds_write2_b32 v211, v194, v146 offset1:16
	v_add_u32_e32 v148, 0x9000, v211
	ds_write2_b32 v102, v179, v111 offset0:64 offset1:80
	v_pk_mul_f32 v[156:157], v[124:125], v[36:37]
	v_pk_mul_f32 v[102:103], v[116:117], v[36:37]
	ds_write2_b32 v114, v160, v104 offset0:128 offset1:144
	v_add_u32_e32 v114, 0xe800, v211
	v_cmp_eq_u32_e64 s[10:11], 0, v220
	v_cmp_ne_u32_e32 vcc, 0, v220
	v_mov_b32_e32 v213, 0
	v_lshl_add_u32 v211, v162, 2, v106
	v_mov_b32_e32 v224, 0
	ds_write2_b32 v148, v203, v159 offset1:16
	ds_write2_b32 v114, v157, v103 offset0:128 offset1:144
	s_waitcnt lgkmcnt(0)
	s_barrier
; __device__ __forceinline__ float erf_f32(float x) {
;   const float ax = fabsf(x);
;   const float t = __frcp_rn(fmaf(0.3275911f, ax, 1.0f));
;   float poly = fmaf(1.061405429f, t, -1.453152027f);
;   poly = fmaf(poly, t, 1.421413741f);
;   poly = fmaf(poly, t, -0.284496736f);
;   poly = fmaf(poly, t, 0.254829592f);
;   const float y = 1.0f - poly * t * __expf(-ax * ax);
; template <int EPI>
; __device__ __forceinline__ void phase_gemm(const Params& p, const GemmDesc& d, char* shmc) {
;     ...
;       float gp[2][4][2], gn[2][4][2];
; #pragma unroll
;       for (int ai = 0; ai < 2; ++ai)
; #pragma unroll
;         for (int m = 0; m < 4; ++m)
; #pragma unroll
;           for (int n = 0; n < 2; ++n) {
;             const int s = ai * 32 + ewr * 16 + m * 4 + efq;
;             const int col = ewc * 32 + n * 16 + efr;
;             gp[ai][m][n] = (s > 0) ? bot[(s - 1) * 144 + col] : 0.f;
;             gn[ai][m][n] = (s < 63) ? top[(s + 1) * 144 + col] : 0.f;
;           }
;       float* edge = p.edge + (size_t)pm * 6 * DFF;
; #pragma unroll
;       for (int n = 0; n < 2; ++n) {
;         const int col = ewc * 32 + n * 16 + efr;
;         const int ch = ch0 + col;
;         const float w0 = cw[n][0], w1 = cw[n][1], w2 = cw[n][2], cb = cw[n][3];
; #pragma unroll
;         for (int ai = 0; ai < 2; ++ai)
; #pragma unroll
;           for (int m = 0; m < 4; ++m) {
;             const int s = ai * 32 + ewr * 16 + m * 4 + efq;
;             const f32x4 g = acc[ai][0][m][n];
;             const f32x4 v = acc[ai][1][m][n];
;             const float c0 = w0 * gp[ai][m][n] + w1 * g[0] + w2 * g[1] + cb;
;             const float c1 = w0 * g[0] + w1 * g[1] + w2 * g[2] + cb;
;             const float c2 = w0 * g[1] + w1 * g[2] + w2 * g[3] + cb;
;             const float c3 = w0 * g[2] + w1 * g[3] + w2 * gn[ai][m][n] + cb;
;             u16* sp = stg + (s * 4) * 136 + col;
;             sp[0] = f2bf(gelu_exact(c0) * v[0]);
;             sp[136] = f2bf(gelu_exact(c1) * v[1]);
;             sp[272] = f2bf(gelu_exact(c2) * v[2]);
;             sp[408] = f2bf(gelu_exact(c3) * v[3]);
;             if (s == 0) {
;               edge[0 * DFF + ch] = c0; edge[1 * DFF + ch] = g[0]; edge[2 * DFF + ch] = v[0];
;             }
;             if (s == 63) {
;               edge[3 * DFF + ch] = c3; edge[4 * DFF + ch] = g[3]; edge[5 * DFF + ch] = v[3];
;             }
;           }
	s_and_saveexec_b64 s[8:9], vcc
	ds_read_b32 v224, v211 offset:36288
	s_or_b64 exec, exec, s[8:9]
	ds_read_b32 v223, v211 offset:576
	s_and_saveexec_b64 s[8:9], vcc
	ds_read_b32 v213, v211 offset:36352
	s_or_b64 exec, exec, s[8:9]
	v_add_u32_e32 v106, 0x9400, v211
	ds_read2_b32 v[150:151], v106 offset0:176 offset1:192
	v_add_u32_e32 v106, 0x800, v211
	ds_read2_b32 v[148:149], v106 offset0:208 offset1:224
	v_add_u32_e32 v106, 0x9e00, v211
	ds_read2_b32 v[140:141], v106 offset0:112 offset1:128
	v_add_u32_e32 v106, 0x1400, v211
	ds_read2_b32 v[138:139], v106 offset0:16 offset1:32
	v_add_u32_e32 v106, 0xa800, v211
	ds_read2_b32 v[132:133], v106 offset0:48 offset1:64
	v_add_u32_e32 v106, 0x1c00, v211
	ds_read2_b32 v[130:131], v106 offset0:80 offset1:96
	v_add_u32_e32 v106, 0xd400, v211
	ds_read2_b32 v[124:125], v106 offset0:112 offset1:128
	v_add_u32_e32 v106, 0x4800, v211
	ds_read2_b32 v[122:123], v106 offset0:144 offset1:160
	v_add_u32_e32 v106, 0xdc00, v211
	ds_read2_b32 v[116:117], v106 offset0:176 offset1:192
	v_add_u32_e32 v106, 0x5000, v211
	ds_read2_b32 v[114:115], v106 offset0:208 offset1:224
	v_add_u32_e32 v106, 0xe600, v211
	ds_read2_b32 v[108:109], v106 offset0:112 offset1:128
	v_add_u32_e32 v106, 0x5c00, v211
	ds_read2_b32 v[106:107], v106 offset0:16 offset1:32
	ds_read_b32 v214, v211 offset:640
	ds_read_b32 v221, v211 offset:61632
	v_cmp_eq_u32_e64 s[8:9], 19, v220
	v_cmp_ne_u32_e32 vcc, 19, v220
	v_add_u32_e32 v222, 0x6300, v211
	v_mov_b32_e32 v211, 0
	v_mov_b32_e32 v219, 0
	s_and_saveexec_b64 s[56:57], vcc
	ds_read_b32 v219, v222 offset:576
	s_or_b64 exec, exec, s[56:57]
	ds_read_b32 v212, v222 offset:36352
	s_and_saveexec_b64 s[56:57], vcc
	ds_read_b32 v211, v222 offset:640
	s_or_b64 exec, exec, s[56:57]
	s_mul_hi_i32 s34, s14, 0x21000
	s_mul_i32 s14, s14, 0x21000
	v_readlane_b32 s56, v246, 15
	v_readlane_b32 s57, v246, 16
	s_add_u32 s56, s56, s14
	s_addc_u32 s57, s57, s34
	v_pk_mul_f32 v[226:227], v[96:97], v[64:65]
	v_pk_mul_f32 v[96:97], v[94:95], v[62:63]
	v_lshl_add_u64 v[94:95], v[200:201], 2, s[56:57]
	s_waitcnt lgkmcnt(14)
	s_waitcnt vmcnt(0)
	v_fma_f32 v200, v215, v224, v218
	v_fmac_f32_e32 v200, v217, v194
	v_mul_f32_e32 v224, v217, v202
	v_fmac_f32_e32 v200, v216, v195
	v_fma_f32 v201, v217, v195, v218
	v_fmac_f32_e32 v224, v215, v195
	v_fmac_f32_e32 v201, v215, v194
	v_fmac_f32_e32 v224, v216, v203
	v_fma_f32 v203, v217, v203, v218
	v_fmac_f32_e32 v201, v216, v202
	v_fmac_f32_e32 v203, v215, v202
	v_mul_f32_e32 v202, 0x3f596d27, v200
	v_fmac_f32_e32 v203, v216, v223
	v_fma_f32 v223, |v202|, s98, 1.0
	v_add_f32_e32 v195, v218, v224
	v_mul_f32_e32 v229, 0.5, v200
	s_add_i32 s14, 0, 0x12000
	v_rcp_f32_e32 v223, v223
	v_mul_f32_e64 v225, |v202|, -|v202|
	v_fmamk_f32 v224, v223, 0x3f87dc22, v206
	v_fmaak_f32 v224, v224, v223, 0x3fb5f0e3
	v_exp_f32_e32 v225, v225
	v_fmaak_f32 v224, v224, v223, 0xbe91a98e
	v_fmaak_f32 v224, v224, v223, 0x3e827906
	v_mul_f32_e32 v223, v223, v224
	v_fma_f32 v202, -v225, v223, 1.0
	v_mul_f32_e32 v223, 0x3f596d27, v201
	v_fma_f32 v224, |v223|, s98, 1.0
	v_fma_f32 v202, |v229|, v202, v229
	v_lshl_add_u32 v222, v162, 1, s14
	v_mul_f32_e32 v202, v96, v202
	v_mad_u32_u24 v228, v220, s84, v222
	v_cvt_pk_bf16_f32 v202, v202, s0
	ds_write_b16 v228, v202
	v_rcp_f32_e32 v202, v224
	v_mul_f32_e64 v225, |v223|, -|v223|
	v_fmamk_f32 v224, v202, 0x3f87dc22, v206
	v_fmaak_f32 v224, v224, v202, 0x3fb5f0e3
	v_exp_f32_e32 v225, v225
	v_fmaak_f32 v224, v224, v202, 0xbe91a98e
	v_fmaak_f32 v224, v224, v202, 0x3e827906
	v_mul_f32_e32 v202, v202, v224
	v_fma_f32 v202, -v225, v202, 1.0
	v_mul_f32_e32 v201, 0.5, v201
	v_fma_f32 v201, |v201|, v202, v201
	v_mul_f32_e32 v97, v97, v201
	v_mul_f32_e32 v201, 0x3f596d27, v195
	v_fma_f32 v202, |v201|, s98, 1.0
	v_cvt_pk_bf16_f32 v97, v97, s0
	ds_write_b16 v228, v97 offset:272
	v_mul_f32_e32 v97, 0.5, v195
	v_rcp_f32_e32 v195, v202
	v_mul_f32_e64 v223, |v201|, -|v201|
	v_fmamk_f32 v202, v195, 0x3f87dc22, v206
	v_fmaak_f32 v202, v202, v195, 0x3fb5f0e3
	v_exp_f32_e32 v223, v223
	v_fmaak_f32 v202, v202, v195, 0xbe91a98e
	v_fmaak_f32 v202, v202, v195, 0x3e827906
	v_mul_f32_e32 v195, v195, v202
	v_fma_f32 v195, -v223, v195, 1.0
	v_fma_f32 v97, |v97|, v195, v97
	v_mul_f32_e32 v195, 0x3f596d27, v203
	v_fma_f32 v201, |v195|, s98, 1.0
	v_mul_f32_e32 v97, v226, v97
	v_cvt_pk_bf16_f32 v97, v97, s0
	ds_write_b16 v228, v97 offset:544
	v_mul_f32_e32 v97, 0.5, v203
	v_rcp_f32_e32 v201, v201
	v_mul_f32_e64 v203, |v195|, -|v195|
	v_fmamk_f32 v202, v201, 0x3f87dc22, v206
	v_fmaak_f32 v202, v202, v201, 0x3fb5f0e3
	v_exp_f32_e32 v203, v203
	v_fmaak_f32 v202, v202, v201, 0xbe91a98e
	v_fmaak_f32 v202, v202, v201, 0x3e827906
	v_mul_f32_e32 v201, v201, v202
	v_fma_f32 v195, -v203, v201, 1.0
	v_fma_f32 v97, |v97|, v195, v97
	v_mul_f32_e32 v97, v227, v97
	v_readlane_b32 s58, v246, 17
	v_readlane_b32 s59, v246, 18
	v_cvt_pk_bf16_f32 v97, v97, s0
	ds_write_b16 v228, v97 offset:816
	s_and_saveexec_b64 s[58:59], s[10:11]
	s_cbranch_execz .LBB0_1166
	global_store_dword v[94:95], v200, off
	v_add_co_u32_e32 v200, vcc, 0x5000, v94
	s_nop 1
	v_addc_co_u32_e32 v201, vcc, 0, v95, vcc
	global_store_dword v[200:201], v194, off offset:2048
	v_add_co_u32_e32 v194, vcc, 0xb000, v94
	s_nop 1
	v_addc_co_u32_e32 v195, vcc, 0, v95, vcc
	global_store_dword v[194:195], v96, off
